# summary tile loop: five adjacent scalar fp32 pairs packed, remaining three v_max folded (clamp form / direct sqrt): 8 VALU fewer per tile
# baseline (speedup 1.0000x reference)
.LBB0_428:
	v_mov_b32_e32 v105, v104
	v_mov_b32_e32 v106, v104
	v_mov_b32_e32 v107, v104
	v_mov_b32_e32 v97, v96
	v_mov_b32_e32 v98, v96
	s_waitcnt lgkmcnt(7)
	v_mfma_f32_16x16x32_bf16 v[114:117], v[24:27], v[56:59], v[104:107]
	v_mov_b32_e32 v99, v96
	v_add_u32_e32 v18, s34, v186
	v_lshl_add_u32 v5, v18, 1, v189
	v_mfma_f32_16x16x32_bf16 v[118:121], v[24:27], v[60:63], v[96:99]
	s_waitcnt lgkmcnt(6)
	v_mfma_f32_16x16x32_bf16 v[128:131], v[28:31], v[64:67], v[114:117]
	s_waitcnt lgkmcnt(5)
	v_mfma_f32_16x16x32_bf16 v[114:117], v[32:35], v[56:59], v[104:107]
	v_mfma_f32_16x16x32_bf16 v[204:207], v[28:31], v[68:71], v[118:121]
	s_waitcnt lgkmcnt(4)
	v_mfma_f32_16x16x32_bf16 v[218:221], v[36:39], v[64:67], v[114:117]
	ds_read_u16 v7, v5
	ds_read_u16 v17, v5 offset:1040
	ds_read_u16 v19, v5 offset:2080
	s_nop 1
	ds_read_u16 v114, v5 offset:3120
	ds_read_u16 v115, v5 offset:4160
	ds_read_u16 v125, v5 offset:5200
	ds_read_u16 v154, v5 offset:6240
	ds_read_u16 v155, v5 offset:7280
	s_waitcnt lgkmcnt(4)
	v_lshlrev_b32_e32 v123, 16, v114
	s_waitcnt lgkmcnt(3)
	v_lshlrev_b32_e32 v124, 16, v115
	v_mfma_f32_16x16x32_bf16 v[118:121], v[32:35], v[60:63], v[96:99]
	v_lshlrev_b32_e32 v126, 16, v7
	v_lshlrev_b32_e32 v127, 16, v17
	v_lshlrev_b32_e32 v122, 16, v19
	v_mfma_f32_16x16x32_bf16 v[114:117], v[40:43], v[56:59], v[104:107]
	s_waitcnt lgkmcnt(2)
	v_lshlrev_b32_e32 v125, 16, v125
	v_mfma_f32_16x16x32_bf16 v[226:229], v[40:43], v[60:63], v[96:99]
	v_mfma_f32_16x16x32_bf16 v[106:109], v[48:51], v[56:59], v[104:107]
	v_exp_f32_e32 v110, v128
	v_exp_f32_e32 v111, v129
	v_mfma_f32_16x16x32_bf16 v[96:99], v[48:51], v[60:63], v[96:99]
	v_exp_f32_e32 v102, v204
	v_exp_f32_e32 v103, v205
	v_pk_add_f32 v[100:101], v[110:111], 1.0 op_sel_hi:[1,0]
	v_mfma_f32_16x16x32_bf16 v[222:225], v[36:39], v[68:71], v[118:121]
	v_rcp_f32_e32 v100, v100
	v_rcp_f32_e32 v101, v101
	v_mfma_f32_16x16x32_bf16 v[226:229], v[44:47], v[68:71], v[226:229]
	s_waitcnt lgkmcnt(1)
	v_lshlrev_b32_e32 v120, 16, v154
	s_waitcnt lgkmcnt(0)
	v_lshlrev_b32_e32 v121, 16, v155
	ds_read_u16 v7, v5 offset:8320
	ds_read_u16 v17, v5 offset:9360
	ds_read_u16 v19, v5 offset:10400
	ds_read_u16 v154, v5 offset:11440
	ds_read_u16 v155, v5 offset:12480
	ds_read_u16 v203, v5 offset:13520
	ds_read_u16 v208, v5 offset:14560
	ds_read_u16 v5, v5 offset:15600
	v_mfma_f32_16x16x32_bf16 v[88:91], v[52:55], v[68:71], v[96:99]
	v_exp_f32_e32 v209, v229
	s_waitcnt lgkmcnt(7)
	v_lshlrev_b32_e32 v118, 16, v7
	s_waitcnt lgkmcnt(1)
	v_lshlrev_b32_e32 v104, 16, v208
	v_pk_add_f32 v[98:99], v[102:103], 1.0 op_sel_hi:[1,0]
	v_exp_f32_e32 v102, v130
	v_exp_f32_e32 v103, v131
	v_pk_mul_f32 v[96:97], v[100:101], v[6:7] op_sel_hi:[1,0]
	v_mfma_f32_16x16x32_bf16 v[230:233], v[44:47], v[64:67], v[114:117]
	v_exp_f32_e32 v96, v96
	v_pk_add_f32 v[102:103], v[102:103], 1.0 op_sel_hi:[1,0]
	v_exp_f32_e32 v97, v97
	v_rcp_f32_e32 v102, v102
	v_rcp_f32_e32 v103, v103
	s_waitcnt lgkmcnt(0)
	v_lshlrev_b32_e32 v105, 16, v5
	v_pk_fma_f32 v[100:101], v[96:97], v[96:97], 1.0 op_sel_hi:[1,1,0] neg_lo:[1,0,0] neg_hi:[1,0,0] clamp
	v_mfma_f32_16x16x32_bf16 v[92:95], v[52:55], v[64:67], v[106:109]
	v_pk_mul_f32 v[102:103], v[102:103], v[6:7] op_sel_hi:[1,0]
	v_exp_f32_e32 v110, v102
	v_exp_f32_e32 v111, v103
	v_exp_f32_e32 v102, v218
	s_cmpk_eq_i32 s30, 0x1800
	s_cbranch_scc1 .Lsl_skip1
	v_lshl_add_u64 v[64:65], v[242:243], 0, s[30:31]
	v_lshl_add_u64 v[68:69], v[244:245], 0, s[30:31]
	v_add_u32_e32 v197, s39, v193
	v_add_u32_e32 v199, s39, v194
	global_load_dwordx4 v[56:59], v[64:65], off offset:2048
	global_load_dwordx4 v[60:63], v[68:69], off offset:2048
	v_lshlrev_b32_e32 v197, 2, v197
	v_lshlrev_b32_e32 v199, 2, v199
	global_load_dwordx4 v[64:67], v[64:65], off offset:2112
	s_nop 0
	global_load_dwordx4 v[68:71], v[68:69], off offset:2112
	global_load_dword v198, v197, s[22:23] offset:2112
	s_nop 0
	global_load_dword v197, v197, s[22:23] offset:64
	global_load_dword v199, v199, s[6:7] offset:64

.LBB0_430:
	s_or_b64 exec, exec, s[34:35]
	s_waitcnt lgkmcnt(4)
	v_mov_b32_e32 v17, v16
	v_mov_b32_e32 v18, v16
	v_mov_b32_e32 v19, v16
	v_mov_b32_e32 v5, v4
	v_mov_b32_e32 v6, v4
	v_mfma_f32_16x16x32_bf16 v[220:223], v[24:27], v[72:75], v[16:19]
	s_waitcnt lgkmcnt(0)
	v_mov_b32_e32 v7, v4
	v_mfma_f32_16x16x32_bf16 v[220:223], v[28:31], v[76:79], v[220:223]
	s_nop 0
	v_mfma_f32_16x16x32_bf16 v[224:227], v[24:27], v[80:83], v[4:7]
	v_mfma_f32_16x16x32_bf16 v[224:227], v[28:31], v[84:87], v[224:227]
	s_nop 4
	v_exp_f32_e32 v110, v220
	v_exp_f32_e32 v111, v221
	v_mfma_f32_16x16x32_bf16 v[228:231], v[32:35], v[72:75], v[16:19]
	v_pk_add_f32 v[110:111], v[110:111], 1.0 op_sel_hi:[1,0]
	v_exp_f32_e32 v130, v224
	v_exp_f32_e32 v131, v225
	v_rcp_f32_e32 v110, v110
	v_rcp_f32_e32 v111, v111
	v_mfma_f32_16x16x32_bf16 v[228:231], v[36:39], v[76:79], v[228:231]
	v_pk_add_f32 v[130:131], v[130:131], 1.0 op_sel_hi:[1,0]
	v_exp_f32_e32 v224, v222
	v_pk_mul_f32 v[110:111], v[110:111], v[148:149] op_sel_hi:[1,0]
	v_rcp_f32_e32 v220, v130
	v_rcp_f32_e32 v221, v131
	v_exp_f32_e32 v130, v110
	v_exp_f32_e32 v131, v111
	v_exp_f32_e32 v225, v223
	v_pk_mul_f32 v[110:111], v[220:221], v[126:127]
	v_mfma_f32_16x16x32_bf16 v[220:223], v[40:43], v[72:75], v[16:19]
	v_pk_fma_f32 v[126:127], v[130:131], v[130:131], 1.0 op_sel_hi:[1,1,0] neg_lo:[1,0,0] neg_hi:[1,0,0] clamp
	v_pk_add_f32 v[224:225], v[224:225], 1.0 op_sel_hi:[1,0]
	v_sqrt_f32_e32 v126, v126
	v_mfma_f32_16x16x32_bf16 v[16:19], v[48:51], v[72:75], v[16:19]
	v_exp_f32_e32 v22, v228
	v_exp_f32_e32 v23, v229
	v_sqrt_f32_e32 v127, v127
	v_mfma_f32_16x16x32_bf16 v[232:235], v[32:35], v[80:83], v[4:7]
	v_exp_f32_e32 v226, v226
	v_exp_f32_e32 v227, v227
	v_rcp_f32_e32 v224, v224
	v_mfma_f32_16x16x32_bf16 v[236:239], v[40:43], v[80:83], v[4:7]
	v_rcp_f32_e32 v225, v225
	v_pk_mul_f32 v[110:111], v[110:111], v[126:127]
	v_pk_add_f32 v[240:241], v[226:227], 1.0 op_sel_hi:[1,0]
	v_mfma_f32_16x16x32_bf16 v[4:7], v[48:51], v[80:83], v[4:7]
	v_pk_mul_f32 v[126:127], v[224:225], v[148:149] op_sel_hi:[1,0]
	v_exp_f32_e32 v126, v126
	v_mfma_f32_16x16x32_bf16 v[220:223], v[44:47], v[76:79], v[220:223]
	v_exp_f32_e32 v127, v127
	s_nop 0
	v_pk_fma_f32 v[20:21], v[126:127], v[126:127], 1.0 op_sel_hi:[1,1,0] neg_lo:[1,0,0] neg_hi:[1,0,0] clamp
	v_mfma_f32_16x16x32_bf16 v[10:13], v[52:55], v[76:79], v[16:19]
	v_sqrt_f32_e32 v8, v20
	s_nop 0
	v_pk_add_f32 v[18:19], v[22:23], 1.0 op_sel_hi:[1,0]
	v_mfma_f32_16x16x32_bf16 v[232:235], v[36:39], v[84:87], v[232:235]
	s_nop 2
	v_exp_f32_e32 v10, v10
	v_exp_f32_e32 v11, v11
	v_exp_f32_e32 v12, v12
	v_mfma_f32_16x16x32_bf16 v[224:227], v[44:47], v[84:87], v[236:239]
	v_exp_f32_e32 v13, v13
	v_exp_f32_e32 v22, v232
	v_exp_f32_e32 v23, v233
	v_mfma_f32_16x16x32_bf16 v[14:17], v[52:55], v[84:87], v[4:7]
	v_rcp_f32_e32 v0, v18
	v_rcp_f32_e32 v1, v19
	v_rcp_f32_e32 v236, v240
	v_rcp_f32_e32 v237, v241
	s_cmpk_eq_i32 s30, 0x1800
	s_cbranch_scc1 .Lsl_skip2
	v_lshl_add_u64 v[76:77], v[246:247], 0, s[30:31]
	v_lshl_add_u64 v[84:85], v[248:249], 0, s[30:31]
	v_add_u32_e32 v200, s39, v193
	v_add_u32_e32 v202, s39, v194
	global_load_dwordx4 v[72:75], v[76:77], off offset:2048
	global_load_dwordx4 v[80:83], v[84:85], off offset:2048
	v_lshlrev_b32_e32 v200, 2, v200
	v_lshlrev_b32_e32 v202, 2, v202
	global_load_dwordx4 v[76:79], v[76:77], off offset:2112
	v_add_u32_e32 v200, 0x1000, v200
	global_load_dwordx4 v[84:87], v[84:85], off offset:2112
	global_load_dword v201, v200, s[22:23] offset:2112
	s_nop 0
	global_load_dword v200, v200, s[22:23] offset:64
	global_load_dword v202, v202, s[6:7] offset:2112
.Lsl_skip2:
	v_pk_mul_f32 v[0:1], v[0:1], v[148:149] op_sel_hi:[1,0]
	v_sqrt_f32_e32 v9, v21
	v_exp_f32_e32 v228, v0
	v_exp_f32_e32 v229, v1
	v_pk_add_f32 v[2:3], v[22:23], 1.0 op_sel_hi:[1,0]
	v_exp_f32_e32 v6, v230
	v_rcp_f32_e32 v2, v2
	v_pk_fma_f32 v[4:5], v[228:229], v[228:229], 1.0 op_sel_hi:[1,1,0] neg_lo:[1,0,0] neg_hi:[1,0,0] clamp
	v_rcp_f32_e32 v3, v3
	v_sqrt_f32_e32 v4, v4
	v_sqrt_f32_e32 v5, v5
	v_exp_f32_e32 v7, v231
	v_pk_mul_f32 v[0:1], v[236:237], v[122:123]
	v_pk_mul_f32 v[2:3], v[2:3], v[124:125]
	v_pk_mul_f32 v[0:1], v[0:1], v[8:9]
	v_exp_f32_e32 v8, v220
	v_exp_f32_e32 v9, v221
	v_pk_mul_f32 v[2:3], v[2:3], v[4:5]
	v_exp_f32_e32 v4, v234
	v_exp_f32_e32 v5, v235
	v_pk_add_f32 v[6:7], v[6:7], 1.0 op_sel_hi:[1,0]
	v_pk_add_f32 v[8:9], v[8:9], 1.0 op_sel_hi:[1,0]
	v_rcp_f32_e32 v6, v6
	v_rcp_f32_e32 v7, v7
	v_pk_add_f32 v[4:5], v[4:5], 1.0 op_sel_hi:[1,0]
	v_rcp_f32_e32 v8, v8
	v_rcp_f32_e32 v9, v9
	v_rcp_f32_e32 v4, v4
	v_rcp_f32_e32 v5, v5
	v_pk_mul_f32 v[6:7], v[6:7], v[148:149] op_sel_hi:[1,0]
	v_pk_mul_f32 v[8:9], v[148:149], v[8:9] op_sel_hi:[0,1]
	v_exp_f32_e32 v122, v6
	v_exp_f32_e32 v123, v7
	v_pk_mul_f32 v[4:5], v[4:5], v[120:121]
	v_exp_f32_e32 v120, v8
	v_exp_f32_e32 v121, v9
	v_exp_f32_e32 v8, v222
	v_exp_f32_e32 v9, v223
	v_pk_fma_f32 v[6:7], v[122:123], v[122:123], 1.0 op_sel_hi:[1,1,0] neg_lo:[1,0,0] neg_hi:[1,0,0] clamp
	v_exp_f32_e32 v18, v224
	v_sqrt_f32_e32 v6, v6
	v_sqrt_f32_e32 v7, v7
	v_exp_f32_e32 v19, v225
	v_pk_add_f32 v[8:9], v[8:9], 1.0 op_sel_hi:[1,0]
	v_exp_f32_e32 v20, v226
	v_rcp_f32_e32 v8, v8
	v_rcp_f32_e32 v9, v9
	v_exp_f32_e32 v21, v227
	v_pk_mul_f32 v[4:5], v[4:5], v[6:7]
	v_pk_add_f32 v[6:7], v[18:19], 1.0 op_sel_hi:[1,0]
	v_pk_fma_f32 v[18:19], v[120:121], v[120:121], 1.0 op_sel_hi:[1,1,0] neg_lo:[1,0,0] neg_hi:[1,0,0] clamp
	v_rcp_f32_e32 v6, v6
	v_rcp_f32_e32 v7, v7
	v_pk_mul_f32 v[8:9], v[148:149], v[8:9] op_sel_hi:[0,1]
	v_sqrt_f32_e32 v18, v18
	v_sqrt_f32_e32 v19, v19
	v_exp_f32_e32 v22, v8
	v_exp_f32_e32 v23, v9
	v_pk_add_f32 v[20:21], v[20:21], 1.0 op_sel_hi:[1,0]
	v_pk_mul_f32 v[6:7], v[6:7], v[118:119]
	v_rcp_f32_e32 v20, v20
	v_rcp_f32_e32 v21, v21
	v_pk_mul_f32 v[6:7], v[6:7], v[18:19]
	v_pk_fma_f32 v[18:19], v[22:23], v[22:23], 1.0 op_sel_hi:[1,1,0] neg_lo:[1,0,0] neg_hi:[1,0,0] clamp
	v_pk_add_f32 v[10:11], v[10:11], 1.0 op_sel_hi:[1,0]
	v_pk_mul_f32 v[8:9], v[20:21], v[116:117]
	v_sqrt_f32_e32 v18, v18
	v_sqrt_f32_e32 v19, v19
	v_rcp_f32_e32 v20, v10
	v_rcp_f32_e32 v21, v11
	v_pk_mul_f32 v[10:11], v[8:9], v[18:19]
	v_exp_f32_e32 v8, v14
	v_exp_f32_e32 v9, v15
	v_pk_mul_f32 v[14:15], v[148:149], v[20:21] op_sel_hi:[0,1]
	v_exp_f32_e32 v20, v14
	v_exp_f32_e32 v21, v15
	v_pk_add_f32 v[8:9], v[8:9], 1.0 op_sel_hi:[1,0]
	s_nop 0
	v_rcp_f32_e32 v14, v8
	v_rcp_f32_e32 v15, v9
	v_pk_fma_f32 v[8:9], v[20:21], v[20:21], 1.0 op_sel_hi:[1,1,0] neg_lo:[1,0,0] neg_hi:[1,0,0] clamp
	v_pk_mul_f32 v[14:15], v[14:15], v[114:115]
	v_sqrt_f32_e32 v18, v8
	v_sqrt_f32_e32 v19, v9
	v_pk_add_f32 v[8:9], v[12:13], 1.0 op_sel_hi:[1,0]
	v_exp_f32_e32 v12, v16
	v_rcp_f32_e32 v8, v8
	v_rcp_f32_e32 v9, v9
	v_exp_f32_e32 v13, v17
	v_pk_mul_f32 v[8:9], v[148:149], v[8:9] op_sel_hi:[0,1]
	v_exp_f32_e32 v8, v8
	v_exp_f32_e32 v9, v9
	v_pk_add_f32 v[12:13], v[12:13], 1.0 op_sel_hi:[1,0]
	v_pk_mul_f32 v[14:15], v[14:15], v[18:19]
	v_rcp_f32_e32 v12, v12
	v_pk_fma_f32 v[16:17], v[8:9], v[8:9], 1.0 op_sel_hi:[1,1,0] neg_lo:[1,0,0] neg_hi:[1,0,0] clamp
	v_rcp_f32_e32 v13, v13
	v_sqrt_f32_e32 v16, v16
	v_sqrt_f32_e32 v17, v17
	v_pk_mul_f32 v[12:13], v[12:13], v[104:105]
	s_nop 0
	v_pk_mul_f32 v[12:13], v[12:13], v[16:17]
	s_nop 0
	v_fma_f32 v13, 0, v9, v13
	v_fmac_f32_e32 v12, v8, v13
	v_mul_f32_e32 v8, v9, v8
	v_mul_f32_e32 v18, v21, v8
	v_fma_f32 v15, v21, v12, v15
	v_fmac_f32_e32 v14, v20, v15
	v_mul_f32_e32 v19, v20, v18
	v_mul_f32_e32 v20, v23, v19
	v_fma_f32 v11, v23, v14, v11
	v_fmac_f32_e32 v10, v22, v11
	v_mul_f32_e32 v21, v22, v20
	v_mul_f32_e32 v22, v121, v21
	v_fma_f32 v7, v121, v10, v7
	v_fmac_f32_e32 v6, v120, v7
	v_mul_f32_e32 v23, v120, v22
	v_mul_f32_e32 v104, v123, v23
	v_fma_f32 v5, v123, v6, v5
	v_fmac_f32_e32 v4, v122, v5
	v_mul_f32_e32 v105, v122, v104
	v_mul_f32_e32 v114, v229, v105
	v_fma_f32 v3, v229, v4, v3
	v_fmac_f32_e32 v2, v228, v3
	v_mul_f32_e32 v115, v228, v114
	v_mul_f32_e32 v116, v127, v115
	v_fma_f32 v1, v127, v2, v1
	v_fmac_f32_e32 v0, v126, v1
	v_mul_f32_e32 v117, v126, v116
	v_mul_f32_e32 v118, v131, v117
	v_fma_f32 v111, v131, v0, v111
	v_fmac_f32_e32 v110, v130, v111
	v_mul_f32_e32 v91, v130, v118
	ds_bpermute_b32 v122, v192, v91
	ds_bpermute_b32 v119, v192, v110
	ds_bpermute_b32 v123, v191, v91
	ds_bpermute_b32 v120, v191, v110
	ds_bpermute_b32 v124, v190, v91
	ds_bpermute_b32 v121, v190, v110
	ds_bpermute_b32 v125, v182, v91
	ds_bpermute_b32 v17, v182, v110
	s_and_saveexec_b64 s[34:35], s[40:41]
	s_cbranch_execz .LBB0_425
	s_waitcnt lgkmcnt(6)
	v_fmac_f32_e32 v119, 0, v122
	s_waitcnt lgkmcnt(5)
	v_mul_f32_e32 v16, v122, v123
	s_waitcnt lgkmcnt(4)
	v_fmac_f32_e32 v120, v119, v123
	s_waitcnt lgkmcnt(3)
	v_mul_f32_e32 v16, v16, v124
	s_waitcnt lgkmcnt(2)
	v_fmac_f32_e32 v121, v120, v124
	v_add_co_u32_e32 v120, vcc, 0x1000, v128
	s_waitcnt lgkmcnt(1)
	v_mul_f32_e32 v16, v16, v125
	s_waitcnt lgkmcnt(0)
	v_fmac_f32_e32 v17, v121, v125
	v_addc_co_u32_e32 v121, vcc, 0, v129, vcc
	global_store_dwordx2 v[120:121], v[16:17], off sc1
	s_branch .LBB0_425
